# swiglu epilogue: 8 SSQ loads hoisted into last K iteration + batched xor-reduction
# speedup vs baseline: 1.0189x; 1.0189x over previous
.LBB0_739:
	s_ashr_i32 s59, s58, 31
	s_lshl_b64 s[18:19], s[58:59], 19
	s_add_u32 s60, s16, s18
	s_addc_u32 s61, s33, s19
	s_and_b64 s[18:19], s[6:7], exec
	s_cselect_b32 s59, s61, s67
	s_cselect_b32 s81, s60, s66
	s_ashr_i32 s31, s30, 31
	s_lshl_b64 s[18:19], s[30:31], 19
	s_add_u32 s62, s5, s18
	s_addc_u32 s63, s46, s19
	s_and_b64 s[18:19], s[6:7], exec
	s_cselect_b32 s31, s63, s39
	s_cselect_b32 s82, s62, s38
	s_add_u32 s83, s38, 0x100
	v_mov_b32_e32 v0, 0
	s_addc_u32 s84, s39, 0
	s_mov_b32 s85, -2
	v_mov_b32_e32 v1, v0
	v_mov_b32_e32 v2, v0
	v_mov_b32_e32 v3, v0
	v_mov_b32_e32 v8, v0
	v_mov_b32_e32 v9, v0
	v_mov_b32_e32 v10, v0
	v_mov_b32_e32 v11, v0
	v_mov_b32_e32 v16, v0
	v_mov_b32_e32 v17, v0
	v_mov_b32_e32 v18, v0
	v_mov_b32_e32 v19, v0
	v_mov_b32_e32 v24, v0
	v_mov_b32_e32 v25, v0
	v_mov_b32_e32 v26, v0
	v_mov_b32_e32 v27, v0
	v_mov_b32_e32 v32, v0
	v_mov_b32_e32 v33, v0
	v_mov_b32_e32 v34, v0
	v_mov_b32_e32 v35, v0
	v_mov_b32_e32 v40, v0
	v_mov_b32_e32 v41, v0
	v_mov_b32_e32 v42, v0
	v_mov_b32_e32 v43, v0
	v_mov_b32_e32 v48, v0
	v_mov_b32_e32 v49, v0
	v_mov_b32_e32 v50, v0
	v_mov_b32_e32 v51, v0
	v_mov_b32_e32 v56, v0
	v_mov_b32_e32 v57, v0
	v_mov_b32_e32 v58, v0
	v_mov_b32_e32 v59, v0
	v_mov_b32_e32 v4, v0
	v_mov_b32_e32 v5, v0
	v_mov_b32_e32 v6, v0
	v_mov_b32_e32 v7, v0
	v_mov_b32_e32 v12, v0
	v_mov_b32_e32 v13, v0
	v_mov_b32_e32 v14, v0
	v_mov_b32_e32 v15, v0
	v_mov_b32_e32 v20, v0
	v_mov_b32_e32 v21, v0
	v_mov_b32_e32 v22, v0
	v_mov_b32_e32 v23, v0
	v_mov_b32_e32 v28, v0
	v_mov_b32_e32 v29, v0
	v_mov_b32_e32 v30, v0
	v_mov_b32_e32 v31, v0
	v_mov_b32_e32 v36, v0
	v_mov_b32_e32 v37, v0
	v_mov_b32_e32 v38, v0
	v_mov_b32_e32 v39, v0
	v_mov_b32_e32 v44, v0
	v_mov_b32_e32 v45, v0
	v_mov_b32_e32 v46, v0
	v_mov_b32_e32 v47, v0
	v_mov_b32_e32 v52, v0
	v_mov_b32_e32 v53, v0
	v_mov_b32_e32 v54, v0
	v_mov_b32_e32 v55, v0
	v_mov_b32_e32 v60, v0
	v_mov_b32_e32 v61, v0
	v_mov_b32_e32 v62, v0
	v_mov_b32_e32 v63, v0
	v_mov_b32_e32 v64, v0
	v_mov_b32_e32 v65, v0
	v_mov_b32_e32 v66, v0
	v_mov_b32_e32 v67, v0
	v_mov_b32_e32 v72, v0
	v_mov_b32_e32 v73, v0
	v_mov_b32_e32 v74, v0
	v_mov_b32_e32 v75, v0
	v_mov_b32_e32 v80, v0
	v_mov_b32_e32 v81, v0
	v_mov_b32_e32 v82, v0
	v_mov_b32_e32 v83, v0
	v_mov_b32_e32 v88, v0
	v_mov_b32_e32 v89, v0
	v_mov_b32_e32 v90, v0
	v_mov_b32_e32 v91, v0
	v_mov_b32_e32 v98, v0
	v_mov_b32_e32 v99, v0
	v_mov_b32_e32 v100, v0
	v_mov_b32_e32 v101, v0
	v_mov_b32_e32 v106, v0
	v_mov_b32_e32 v107, v0
	v_mov_b32_e32 v108, v0
	v_mov_b32_e32 v109, v0
	v_mov_b32_e32 v114, v0
	v_mov_b32_e32 v115, v0
	v_mov_b32_e32 v116, v0
	v_mov_b32_e32 v117, v0
	v_mov_b32_e32 v122, v0
	v_mov_b32_e32 v123, v0
	v_mov_b32_e32 v124, v0
	v_mov_b32_e32 v125, v0
	v_mov_b32_e32 v68, v0
	v_mov_b32_e32 v69, v0
	v_mov_b32_e32 v70, v0
	v_mov_b32_e32 v71, v0
	v_mov_b32_e32 v76, v0
	v_mov_b32_e32 v77, v0
	v_mov_b32_e32 v78, v0
	v_mov_b32_e32 v79, v0
	v_mov_b32_e32 v84, v0
	v_mov_b32_e32 v85, v0
	v_mov_b32_e32 v86, v0
	v_mov_b32_e32 v87, v0
	v_mov_b32_e32 v92, v0
	v_mov_b32_e32 v93, v0
	v_mov_b32_e32 v94, v0
	v_mov_b32_e32 v95, v0
	v_mov_b32_e32 v102, v0
	v_mov_b32_e32 v103, v0
	v_mov_b32_e32 v104, v0
	v_mov_b32_e32 v105, v0
	v_mov_b32_e32 v110, v0
	v_mov_b32_e32 v111, v0
	v_mov_b32_e32 v112, v0
	v_mov_b32_e32 v113, v0
	v_mov_b32_e32 v118, v0
	v_mov_b32_e32 v119, v0
	v_mov_b32_e32 v120, v0
	v_mov_b32_e32 v121, v0
	v_mov_b32_e32 v126, v0
	v_mov_b32_e32 v127, v0
	v_mov_b32_e32 v128, v0
	v_mov_b32_e32 v129, v0
	s_lshl_b32 s18, s64, 8
	s_add_i32 s18, s18, s75
	v_and_or_b32 v252, v217, 15, s18
	v_bfe_u32 v253, v217, 4, 2
	v_lshlrev_b32_e32 v252, 6, v252
	v_lshl_add_u32 v252, v253, 4, v252
	v_mov_b32_e32 v253, 0
	v_mov_b64_e32 v[184:185], 0x2000
	v_lshl_add_u64 v[252:253], s[10:11], 0, v[252:253]
	v_lshl_add_u64 v[184:185], v[252:253], 0, v[184:185]
.LBB0_740:
	s_add_u32 s18, s66, 0x80
	s_addc_u32 s19, s67, 0
	s_add_u32 s66, s66, 0x100
	s_addc_u32 s67, s67, 0
	s_cmp_eq_u32 s85, 12
	s_cselect_b32 s42, s81, s66
	s_cselect_b32 s43, s59, s67
	s_cselect_b32 s45, s31, s84
	s_cselect_b32 s44, s82, s83
	s_add_u32 s38, s42, 0x80
	s_addc_u32 s39, s43, 0
	s_add_u32 s68, s44, 0x80
	s_addc_u32 s69, s45, 0
	s_add_i32 s35, 0, 0x10000
	s_add_i32 s49, 0, 0x14000
	v_add_u32_e32 v96, s35, v151
	v_add_u32_e32 v150, s49, v151
	ds_read_b128 v[138:141], v96
	ds_read_b128 v[142:145], v96 offset:1024
	ds_read_b128 v[146:149], v96 offset:2048
	ds_read_b128 v[156:159], v96 offset:3072
	ds_read_b128 v[160:163], v150
	ds_read_b128 v[164:167], v150 offset:1024
	ds_read_b128 v[168:171], v150 offset:2048
	ds_read_b128 v[172:175], v150 offset:3072
	s_add_u32 s18, s18, 0x40000
	s_addc_u32 s19, s19, 0
	v_lshl_add_u64 v[152:153], s[18:19], 0, v[136:137]
	s_add_i32 m0, s65, 0xc000
	ds_read_b128 v[176:179], v155
	ds_read_b128 v[180:183], v155 offset:1024
	ds_read_b128 v[190:193], v155 offset:2048
	ds_read_b128 v[194:197], v155 offset:3072
	ds_read_b128 v[198:201], v155 offset:4096
	ds_read_b128 v[202:205], v155 offset:5120
	ds_read_b128 v[206:209], v155 offset:6144
	ds_read_b128 v[210:213], v155 offset:7168
	global_load_lds_dwordx4 v[152:153], off
	v_lshl_add_u64 v[152:153], s[18:19], 0, v[132:133]
	s_add_i32 m0, s65, 0xe000
	s_nop 0
	global_load_lds_dwordx4 v[152:153], off
	s_waitcnt vmcnt(8)
	s_waitcnt lgkmcnt(0)
	s_barrier
	s_setprio 1
	s_waitcnt lgkmcnt(0)
	v_mfma_f32_16x16x32_bf16 v[126:129], v[138:141], v[176:179], v[126:129]
	v_mfma_f32_16x16x32_bf16 v[118:121], v[146:149], v[176:179], v[118:121]
	v_mfma_f32_16x16x32_bf16 v[110:113], v[138:141], v[190:193], v[110:113]
	v_mfma_f32_16x16x32_bf16 v[102:105], v[146:149], v[190:193], v[102:105]
	v_mfma_f32_16x16x32_bf16 v[92:95], v[138:141], v[198:201], v[92:95]
	v_mfma_f32_16x16x32_bf16 v[84:87], v[146:149], v[198:201], v[84:87]
	v_mfma_f32_16x16x32_bf16 v[76:79], v[138:141], v[206:209], v[76:79]
	v_mfma_f32_16x16x32_bf16 v[68:71], v[146:149], v[206:209], v[68:71]
	v_mfma_f32_16x16x32_bf16 v[126:129], v[142:145], v[180:183], v[126:129]
	v_mfma_f32_16x16x32_bf16 v[118:121], v[156:159], v[180:183], v[118:121]
	v_mfma_f32_16x16x32_bf16 v[110:113], v[142:145], v[194:197], v[110:113]
	v_mfma_f32_16x16x32_bf16 v[102:105], v[156:159], v[194:197], v[102:105]
	v_mfma_f32_16x16x32_bf16 v[92:95], v[142:145], v[202:205], v[92:95]
	v_mfma_f32_16x16x32_bf16 v[84:87], v[156:159], v[202:205], v[84:87]
	v_mfma_f32_16x16x32_bf16 v[76:79], v[142:145], v[210:213], v[76:79]
	v_mfma_f32_16x16x32_bf16 v[68:71], v[156:159], v[210:213], v[68:71]
	s_setprio 0
	s_setprio 1
	v_mfma_f32_16x16x32_bf16 v[122:125], v[160:163], v[176:179], v[122:125]
	v_mfma_f32_16x16x32_bf16 v[114:117], v[168:171], v[176:179], v[114:117]
	v_mfma_f32_16x16x32_bf16 v[106:109], v[160:163], v[190:193], v[106:109]
	v_mfma_f32_16x16x32_bf16 v[98:101], v[168:171], v[190:193], v[98:101]
	v_mfma_f32_16x16x32_bf16 v[88:91], v[160:163], v[198:201], v[88:91]
	v_mfma_f32_16x16x32_bf16 v[80:83], v[168:171], v[198:201], v[80:83]
	v_mfma_f32_16x16x32_bf16 v[72:75], v[160:163], v[206:209], v[72:75]
	v_mfma_f32_16x16x32_bf16 v[64:67], v[168:171], v[206:209], v[64:67]
	v_mfma_f32_16x16x32_bf16 v[122:125], v[164:167], v[180:183], v[122:125]
	v_mfma_f32_16x16x32_bf16 v[114:117], v[172:175], v[180:183], v[114:117]
	v_mfma_f32_16x16x32_bf16 v[106:109], v[164:167], v[194:197], v[106:109]
	v_mfma_f32_16x16x32_bf16 v[98:101], v[172:175], v[194:197], v[98:101]
	v_mfma_f32_16x16x32_bf16 v[88:91], v[164:167], v[202:205], v[88:91]
	v_mfma_f32_16x16x32_bf16 v[80:83], v[172:175], v[202:205], v[80:83]
	v_mfma_f32_16x16x32_bf16 v[72:75], v[164:167], v[210:213], v[72:75]
	v_mfma_f32_16x16x32_bf16 v[64:67], v[172:175], v[210:213], v[64:67]
	s_setprio 0
	s_barrier
	s_add_i32 s18, s35, s47
	v_lshl_add_u64 v[152:153], s[44:45], 0, v[134:135]
	s_mov_b32 m0, s18
	ds_read_b128 v[176:179], v155 offset:16384
	ds_read_b128 v[180:183], v155 offset:17408
	ds_read_b128 v[190:193], v155 offset:18432
	ds_read_b128 v[194:197], v155 offset:19456
	ds_read_b128 v[198:201], v155 offset:20480
	ds_read_b128 v[202:205], v155 offset:21504
	ds_read_b128 v[206:209], v155 offset:22528
	ds_read_b128 v[210:213], v155 offset:23552
	global_load_lds_dwordx4 v[152:153], off
	s_add_i32 m0, s18, 0x2000
	s_add_u32 s18, s44, 0x40000
	v_lshl_add_u64 v[152:153], s[44:45], 0, v[130:131]
	s_addc_u32 s19, s45, 0
	s_add_i32 s35, s49, s47
	global_load_lds_dwordx4 v[152:153], off
	v_lshl_add_u64 v[152:153], s[18:19], 0, v[134:135]
	s_mov_b32 m0, s35
	s_nop 0
	global_load_lds_dwordx4 v[152:153], off
	v_lshl_add_u64 v[152:153], s[18:19], 0, v[130:131]
	s_add_i32 m0, s35, 0x2000
	s_nop 0
	global_load_lds_dwordx4 v[152:153], off
	v_lshl_add_u64 v[152:153], s[42:43], 0, v[136:137]
	s_mov_b32 m0, s65
	s_nop 0
	global_load_lds_dwordx4 v[152:153], off
	v_lshl_add_u64 v[152:153], s[42:43], 0, v[132:133]
	s_mov_b32 m0, s72
	s_nop 0
	global_load_lds_dwordx4 v[152:153], off
	s_waitcnt vmcnt(8)
	s_waitcnt lgkmcnt(0)
	s_barrier
	s_setprio 1
	s_waitcnt lgkmcnt(0)
	v_mfma_f32_16x16x32_bf16 v[60:63], v[138:141], v[176:179], v[60:63]
	v_mfma_f32_16x16x32_bf16 v[52:55], v[146:149], v[176:179], v[52:55]
	v_mfma_f32_16x16x32_bf16 v[44:47], v[138:141], v[190:193], v[44:47]
	v_mfma_f32_16x16x32_bf16 v[36:39], v[146:149], v[190:193], v[36:39]
	v_mfma_f32_16x16x32_bf16 v[28:31], v[138:141], v[198:201], v[28:31]
	v_mfma_f32_16x16x32_bf16 v[20:23], v[146:149], v[198:201], v[20:23]
	v_mfma_f32_16x16x32_bf16 v[12:15], v[138:141], v[206:209], v[12:15]
	v_mfma_f32_16x16x32_bf16 v[4:7], v[146:149], v[206:209], v[4:7]
	v_mfma_f32_16x16x32_bf16 v[60:63], v[142:145], v[180:183], v[60:63]
	v_mfma_f32_16x16x32_bf16 v[52:55], v[156:159], v[180:183], v[52:55]
	v_mfma_f32_16x16x32_bf16 v[44:47], v[142:145], v[194:197], v[44:47]
	v_mfma_f32_16x16x32_bf16 v[36:39], v[156:159], v[194:197], v[36:39]
	v_mfma_f32_16x16x32_bf16 v[28:31], v[142:145], v[202:205], v[28:31]
	v_mfma_f32_16x16x32_bf16 v[20:23], v[156:159], v[202:205], v[20:23]
	v_mfma_f32_16x16x32_bf16 v[12:15], v[142:145], v[210:213], v[12:15]
	v_mfma_f32_16x16x32_bf16 v[4:7], v[156:159], v[210:213], v[4:7]
	s_setprio 0
	s_setprio 1
	v_mfma_f32_16x16x32_bf16 v[56:59], v[160:163], v[176:179], v[56:59]
	v_mfma_f32_16x16x32_bf16 v[48:51], v[168:171], v[176:179], v[48:51]
	v_mfma_f32_16x16x32_bf16 v[40:43], v[160:163], v[190:193], v[40:43]
	v_mfma_f32_16x16x32_bf16 v[32:35], v[168:171], v[190:193], v[32:35]
	v_mfma_f32_16x16x32_bf16 v[24:27], v[160:163], v[198:201], v[24:27]
	v_mfma_f32_16x16x32_bf16 v[16:19], v[168:171], v[198:201], v[16:19]
	v_mfma_f32_16x16x32_bf16 v[8:11], v[160:163], v[206:209], v[8:11]
	v_mfma_f32_16x16x32_bf16 v[0:3], v[168:171], v[206:209], v[0:3]
	v_mfma_f32_16x16x32_bf16 v[56:59], v[164:167], v[180:183], v[56:59]
	v_mfma_f32_16x16x32_bf16 v[48:51], v[172:175], v[180:183], v[48:51]
	v_mfma_f32_16x16x32_bf16 v[40:43], v[164:167], v[194:197], v[40:43]
	v_mfma_f32_16x16x32_bf16 v[32:35], v[172:175], v[194:197], v[32:35]
	v_mfma_f32_16x16x32_bf16 v[24:27], v[164:167], v[202:205], v[24:27]
	v_mfma_f32_16x16x32_bf16 v[16:19], v[172:175], v[202:205], v[16:19]
	v_mfma_f32_16x16x32_bf16 v[8:11], v[164:167], v[210:213], v[8:11]
	v_mfma_f32_16x16x32_bf16 v[0:3], v[172:175], v[210:213], v[0:3]
	s_setprio 0
	s_barrier
	s_add_i32 s35, 0, 0x18000
	v_add_u32_e32 v96, s35, v151
	s_add_i32 s44, 0, 0x1c000
	ds_read_b128 v[138:141], v96
	ds_read_b128 v[142:145], v96 offset:1024
	ds_read_b128 v[146:149], v96 offset:2048
	ds_read_b128 v[156:159], v96 offset:3072
	v_add_u32_e32 v96, s44, v151
	ds_read_b128 v[160:163], v96
	ds_read_b128 v[164:167], v96 offset:1024
	ds_read_b128 v[168:171], v96 offset:2048
	ds_read_b128 v[172:175], v96 offset:3072
	s_add_u32 s18, s42, 0x40000
	s_addc_u32 s19, s43, 0
	s_mov_b32 m0, s73
	v_lshl_add_u64 v[152:153], s[18:19], 0, v[136:137]
	ds_read_b128 v[176:179], v155 offset:32768
	ds_read_b128 v[180:183], v155 offset:33792
	ds_read_b128 v[190:193], v155 offset:34816
	ds_read_b128 v[194:197], v155 offset:35840
	ds_read_b128 v[198:201], v155 offset:36864
	ds_read_b128 v[202:205], v155 offset:37888
	ds_read_b128 v[206:209], v155 offset:38912
	ds_read_b128 v[210:213], v155 offset:39936
	global_load_lds_dwordx4 v[152:153], off
	v_lshl_add_u64 v[152:153], s[18:19], 0, v[132:133]
	s_mov_b32 m0, s74
	s_nop 0
	global_load_lds_dwordx4 v[152:153], off
	s_waitcnt vmcnt(8)
	s_waitcnt lgkmcnt(0)
	s_barrier
	s_setprio 1
	s_waitcnt lgkmcnt(0)
	v_mfma_f32_16x16x32_bf16 v[126:129], v[138:141], v[176:179], v[126:129]
	v_mfma_f32_16x16x32_bf16 v[118:121], v[146:149], v[176:179], v[118:121]
	v_mfma_f32_16x16x32_bf16 v[110:113], v[138:141], v[190:193], v[110:113]
	v_mfma_f32_16x16x32_bf16 v[102:105], v[146:149], v[190:193], v[102:105]
	v_mfma_f32_16x16x32_bf16 v[92:95], v[138:141], v[198:201], v[92:95]
	v_mfma_f32_16x16x32_bf16 v[84:87], v[146:149], v[198:201], v[84:87]
	v_mfma_f32_16x16x32_bf16 v[76:79], v[138:141], v[206:209], v[76:79]
	v_mfma_f32_16x16x32_bf16 v[68:71], v[146:149], v[206:209], v[68:71]
	v_mfma_f32_16x16x32_bf16 v[126:129], v[142:145], v[180:183], v[126:129]
	v_mfma_f32_16x16x32_bf16 v[118:121], v[156:159], v[180:183], v[118:121]
	v_mfma_f32_16x16x32_bf16 v[110:113], v[142:145], v[194:197], v[110:113]
	v_mfma_f32_16x16x32_bf16 v[102:105], v[156:159], v[194:197], v[102:105]
	v_mfma_f32_16x16x32_bf16 v[92:95], v[142:145], v[202:205], v[92:95]
	v_mfma_f32_16x16x32_bf16 v[84:87], v[156:159], v[202:205], v[84:87]
	v_mfma_f32_16x16x32_bf16 v[76:79], v[142:145], v[210:213], v[76:79]
	v_mfma_f32_16x16x32_bf16 v[68:71], v[156:159], v[210:213], v[68:71]
	s_setprio 0
	s_setprio 1
	v_mfma_f32_16x16x32_bf16 v[122:125], v[160:163], v[176:179], v[122:125]
	v_mfma_f32_16x16x32_bf16 v[114:117], v[168:171], v[176:179], v[114:117]
	v_mfma_f32_16x16x32_bf16 v[106:109], v[160:163], v[190:193], v[106:109]
	v_mfma_f32_16x16x32_bf16 v[98:101], v[168:171], v[190:193], v[98:101]
	v_mfma_f32_16x16x32_bf16 v[88:91], v[160:163], v[198:201], v[88:91]
	v_mfma_f32_16x16x32_bf16 v[80:83], v[168:171], v[198:201], v[80:83]
	v_mfma_f32_16x16x32_bf16 v[72:75], v[160:163], v[206:209], v[72:75]
	v_mfma_f32_16x16x32_bf16 v[64:67], v[168:171], v[206:209], v[64:67]
	v_mfma_f32_16x16x32_bf16 v[122:125], v[164:167], v[180:183], v[122:125]
	v_mfma_f32_16x16x32_bf16 v[114:117], v[172:175], v[180:183], v[114:117]
	v_mfma_f32_16x16x32_bf16 v[106:109], v[164:167], v[194:197], v[106:109]
	v_mfma_f32_16x16x32_bf16 v[98:101], v[172:175], v[194:197], v[98:101]
	v_mfma_f32_16x16x32_bf16 v[88:91], v[164:167], v[202:205], v[88:91]
	v_mfma_f32_16x16x32_bf16 v[80:83], v[172:175], v[202:205], v[80:83]
	v_mfma_f32_16x16x32_bf16 v[72:75], v[164:167], v[210:213], v[72:75]
	v_mfma_f32_16x16x32_bf16 v[64:67], v[172:175], v[210:213], v[64:67]
	s_setprio 0
	s_barrier
	s_add_i32 s18, s35, s47
	v_lshl_add_u64 v[152:153], s[68:69], 0, v[134:135]
	s_mov_b32 m0, s18
	ds_read_b128 v[176:179], v155 offset:49152
	ds_read_b128 v[180:183], v155 offset:50176
	ds_read_b128 v[190:193], v155 offset:51200
	ds_read_b128 v[194:197], v155 offset:52224
	ds_read_b128 v[198:201], v155 offset:53248
	ds_read_b128 v[202:205], v155 offset:54272
	ds_read_b128 v[206:209], v155 offset:55296
	ds_read_b128 v[210:213], v155 offset:56320
	global_load_lds_dwordx4 v[152:153], off
	s_add_i32 m0, s18, 0x2000
	s_add_u32 s18, s68, 0x40000
	v_lshl_add_u64 v[152:153], s[68:69], 0, v[130:131]
	s_addc_u32 s19, s69, 0
	s_add_i32 s35, s44, s47
	global_load_lds_dwordx4 v[152:153], off
	v_lshl_add_u64 v[152:153], s[18:19], 0, v[134:135]
	s_mov_b32 m0, s35
	s_nop 0
	global_load_lds_dwordx4 v[152:153], off
	v_lshl_add_u64 v[152:153], s[18:19], 0, v[130:131]
	s_add_i32 m0, s35, 0x2000
	s_nop 0
	global_load_lds_dwordx4 v[152:153], off
	v_lshl_add_u64 v[152:153], s[38:39], 0, v[136:137]
	s_mov_b32 m0, s77
	s_nop 0
	global_load_lds_dwordx4 v[152:153], off
	v_lshl_add_u64 v[152:153], s[38:39], 0, v[132:133]
	s_mov_b32 m0, s78
	s_nop 0
	global_load_lds_dwordx4 v[152:153], off
	s_waitcnt vmcnt(8)
	s_cmp_lg_u32 s85, 12
	s_cbranch_scc1 .Lswi_ssq_skip
	global_load_dwordx4 v[220:223], v[252:253], off
	global_load_dwordx4 v[224:227], v[252:253], off offset:1024
	global_load_dwordx4 v[228:231], v[252:253], off offset:2048
	global_load_dwordx4 v[232:235], v[252:253], off offset:3072
	global_load_dwordx4 v[236:239], v[184:185], off
	global_load_dwordx4 v[240:243], v[184:185], off offset:1024
	global_load_dwordx4 v[244:247], v[184:185], off offset:2048
	global_load_dwordx4 v[248:251], v[184:185], off offset:3072
.Lswi_ssq_skip:
	s_waitcnt lgkmcnt(0)
	s_barrier
	s_setprio 1
	s_waitcnt lgkmcnt(0)
	v_mfma_f32_16x16x32_bf16 v[60:63], v[138:141], v[176:179], v[60:63]
	v_mfma_f32_16x16x32_bf16 v[52:55], v[146:149], v[176:179], v[52:55]
	v_mfma_f32_16x16x32_bf16 v[44:47], v[138:141], v[190:193], v[44:47]
	v_mfma_f32_16x16x32_bf16 v[36:39], v[146:149], v[190:193], v[36:39]
	v_mfma_f32_16x16x32_bf16 v[28:31], v[138:141], v[198:201], v[28:31]
	v_mfma_f32_16x16x32_bf16 v[20:23], v[146:149], v[198:201], v[20:23]
	v_mfma_f32_16x16x32_bf16 v[12:15], v[138:141], v[206:209], v[12:15]
	v_mfma_f32_16x16x32_bf16 v[4:7], v[146:149], v[206:209], v[4:7]
	v_mfma_f32_16x16x32_bf16 v[60:63], v[142:145], v[180:183], v[60:63]
	v_mfma_f32_16x16x32_bf16 v[52:55], v[156:159], v[180:183], v[52:55]
	v_mfma_f32_16x16x32_bf16 v[44:47], v[142:145], v[194:197], v[44:47]
	v_mfma_f32_16x16x32_bf16 v[36:39], v[156:159], v[194:197], v[36:39]
	v_mfma_f32_16x16x32_bf16 v[28:31], v[142:145], v[202:205], v[28:31]
	v_mfma_f32_16x16x32_bf16 v[20:23], v[156:159], v[202:205], v[20:23]
	v_mfma_f32_16x16x32_bf16 v[12:15], v[142:145], v[210:213], v[12:15]
	v_mfma_f32_16x16x32_bf16 v[4:7], v[156:159], v[210:213], v[4:7]
	s_setprio 0
	s_setprio 1
	v_mfma_f32_16x16x32_bf16 v[56:59], v[160:163], v[176:179], v[56:59]
	v_mfma_f32_16x16x32_bf16 v[48:51], v[168:171], v[176:179], v[48:51]
	v_mfma_f32_16x16x32_bf16 v[40:43], v[160:163], v[190:193], v[40:43]
	v_mfma_f32_16x16x32_bf16 v[32:35], v[168:171], v[190:193], v[32:35]
	v_mfma_f32_16x16x32_bf16 v[24:27], v[160:163], v[198:201], v[24:27]
	v_mfma_f32_16x16x32_bf16 v[16:19], v[168:171], v[198:201], v[16:19]
	v_mfma_f32_16x16x32_bf16 v[8:11], v[160:163], v[206:209], v[8:11]
	v_mfma_f32_16x16x32_bf16 v[0:3], v[168:171], v[206:209], v[0:3]
	v_mfma_f32_16x16x32_bf16 v[56:59], v[164:167], v[180:183], v[56:59]
	v_mfma_f32_16x16x32_bf16 v[48:51], v[172:175], v[180:183], v[48:51]
	v_mfma_f32_16x16x32_bf16 v[40:43], v[164:167], v[194:197], v[40:43]
	v_mfma_f32_16x16x32_bf16 v[32:35], v[172:175], v[194:197], v[32:35]
	v_mfma_f32_16x16x32_bf16 v[24:27], v[164:167], v[202:205], v[24:27]
	v_mfma_f32_16x16x32_bf16 v[16:19], v[172:175], v[202:205], v[16:19]
	v_mfma_f32_16x16x32_bf16 v[8:11], v[164:167], v[210:213], v[8:11]
	v_mfma_f32_16x16x32_bf16 v[0:3], v[172:175], v[210:213], v[0:3]
	s_setprio 0
	s_barrier
	s_add_i32 s85, s85, 2
	s_add_u32 s83, s83, 0x100
	s_addc_u32 s84, s84, 0
	s_cmp_gt_u32 s85, 13
	s_cbranch_scc0 .LBB0_740
	s_and_b64 vcc, exec, s[28:29]
	s_cbranch_vccz .LBB0_743
	s_barrier
.LBB0_743:
	s_lshl_b32 s18, s64, 8
	s_add_i32 s18, s18, s75
	v_mbcnt_lo_u32_b32 v96, -1, 0
	v_mbcnt_hi_u32_b32 v96, -1, v96
	s_mov_b64 s[38:39], -1
	v_bfe_u32 v138, v96, 4, 2
	v_and_or_b32 v160, v96, 15, s18
	s_lshl_b32 s18, s80, 7
	v_lshl_or_b32 v96, v138, 3, s18
	v_or_b32_e32 v162, s76, v96
	v_ashrrev_i32_e32 v163, 31, v162
	v_or_b32_e32 v156, 16, v160
	v_or_b32_e32 v152, 32, v160
	v_or_b32_e32 v148, 48, v160
	v_add_u32_e32 v144, 0x80, v160
	v_add_u32_e32 v142, 0x90, v160
	v_add_u32_e32 v140, 0xa0, v160
	v_add_u32_e32 v138, 0xb0, v160
	v_and_b32_e32 v147, 64, v217
	v_xor_b32_e32 v146, 16, v217
	v_add_u32_e32 v147, 64, v147
	v_cmp_lt_i32_e32 vcc, v146, v147
	s_nop 1
	v_cndmask_b32_e32 v146, v217, v146, vcc
	v_lshlrev_b32_e32 v157, 2, v146
	v_xor_b32_e32 v146, 32, v217
	v_cmp_lt_i32_e32 vcc, v146, v147
	s_nop 1
	v_cndmask_b32_e32 v146, v217, v146, vcc
	v_lshlrev_b32_e32 v147, 2, v146
	s_nop 0
	s_andn2_b64 vcc, exec, s[6:7]
	s_waitcnt vmcnt(0)
	v_add_f32_e32 v220, v221, v220
	v_add_f32_e32 v222, v222, v223
	v_add_f32_e32 v224, v225, v224
	v_add_f32_e32 v226, v226, v227
	v_add_f32_e32 v228, v229, v228
	v_add_f32_e32 v230, v230, v231
	v_add_f32_e32 v232, v233, v232
	v_add_f32_e32 v234, v234, v235
	v_add_f32_e32 v236, v237, v236
	v_add_f32_e32 v238, v238, v239
	v_add_f32_e32 v240, v241, v240
	v_add_f32_e32 v242, v242, v243
	v_add_f32_e32 v244, v245, v244
	v_add_f32_e32 v246, v246, v247
	v_add_f32_e32 v248, v249, v248
	v_add_f32_e32 v250, v250, v251
	v_add_f32_e32 v220, v220, v222
	v_add_f32_e32 v224, v224, v226
	v_add_f32_e32 v228, v228, v230
	v_add_f32_e32 v232, v232, v234
	v_add_f32_e32 v236, v236, v238
	v_add_f32_e32 v240, v240, v242
	v_add_f32_e32 v244, v244, v246
	v_add_f32_e32 v248, v248, v250
	ds_bpermute_b32 v221, v157, v220
	ds_bpermute_b32 v225, v157, v224
	ds_bpermute_b32 v229, v157, v228
	ds_bpermute_b32 v233, v157, v232
	ds_bpermute_b32 v237, v157, v236
	ds_bpermute_b32 v241, v157, v240
	ds_bpermute_b32 v245, v157, v244
	ds_bpermute_b32 v249, v157, v248
	s_waitcnt lgkmcnt(7)
	v_add_f32_e32 v220, v220, v221
	ds_bpermute_b32 v221, v147, v220
	s_waitcnt lgkmcnt(7)
	v_add_f32_e32 v224, v224, v225
	ds_bpermute_b32 v225, v147, v224
	s_waitcnt lgkmcnt(7)
	v_add_f32_e32 v228, v228, v229
	ds_bpermute_b32 v229, v147, v228
	s_waitcnt lgkmcnt(7)
	v_add_f32_e32 v232, v232, v233
	ds_bpermute_b32 v233, v147, v232
	s_waitcnt lgkmcnt(7)
	v_add_f32_e32 v236, v236, v237
	ds_bpermute_b32 v237, v147, v236
	s_waitcnt lgkmcnt(7)
	v_add_f32_e32 v240, v240, v241
	ds_bpermute_b32 v241, v147, v240
	s_waitcnt lgkmcnt(7)
	v_add_f32_e32 v244, v244, v245
	ds_bpermute_b32 v245, v147, v244
	s_waitcnt lgkmcnt(7)
	v_add_f32_e32 v248, v248, v249
	ds_bpermute_b32 v249, v147, v248
	s_waitcnt lgkmcnt(7)
	v_add_f32_e32 v220, v220, v221
	v_fmamk_f32 v220, v220, 0x3a800000, v216
	s_waitcnt lgkmcnt(6)
	v_add_f32_e32 v224, v224, v225
	v_fmamk_f32 v224, v224, 0x3a800000, v216
	s_waitcnt lgkmcnt(5)
	v_add_f32_e32 v228, v228, v229
	v_fmamk_f32 v228, v228, 0x3a800000, v216
	s_waitcnt lgkmcnt(4)
	v_add_f32_e32 v232, v232, v233
	v_fmamk_f32 v232, v232, 0x3a800000, v216
	s_waitcnt lgkmcnt(3)
	v_add_f32_e32 v236, v236, v237
	v_fmamk_f32 v236, v236, 0x3a800000, v216
	s_waitcnt lgkmcnt(2)
	v_add_f32_e32 v240, v240, v241
	v_fmamk_f32 v240, v240, 0x3a800000, v216
	s_waitcnt lgkmcnt(1)
	v_add_f32_e32 v244, v244, v245
	v_fmamk_f32 v244, v244, 0x3a800000, v216
	s_waitcnt lgkmcnt(0)
	v_add_f32_e32 v248, v248, v249
	v_fmamk_f32 v248, v248, 0x3a800000, v216
	v_rsq_f32_e32 v168, v220
	v_rsq_f32_e32 v166, v224
	v_rsq_f32_e32 v164, v228
	v_rsq_f32_e32 v158, v232
	v_rsq_f32_e32 v154, v236
	v_rsq_f32_e32 v150, v240
	v_rsq_f32_e32 v146, v244
	v_rsq_f32_e32 v96, v248
	s_nop 0
	v_pk_mul_f32 v[126:127], v[126:127], v[168:169] op_sel_hi:[1,0]
	v_pk_mul_f32 v[122:123], v[122:123], v[168:169] op_sel_hi:[1,0]
	v_pk_mul_f32 v[124:125], v[124:125], v[168:169] op_sel_hi:[1,0]
	v_pk_mul_f32 v[118:119], v[118:119], v[168:169] op_sel_hi:[1,0]
	v_pk_mul_f32 v[114:115], v[114:115], v[168:169] op_sel_hi:[1,0]
	v_pk_mul_f32 v[116:117], v[116:117], v[168:169] op_sel_hi:[1,0]
	v_pk_mul_f32 v[110:111], v[110:111], v[166:167] op_sel_hi:[1,0]
	v_pk_mul_f32 v[106:107], v[106:107], v[166:167] op_sel_hi:[1,0]
	v_pk_mul_f32 v[108:109], v[108:109], v[166:167] op_sel_hi:[1,0]
	v_pk_mul_f32 v[102:103], v[102:103], v[166:167] op_sel_hi:[1,0]
	v_pk_mul_f32 v[98:99], v[98:99], v[166:167] op_sel_hi:[1,0]
	v_pk_mul_f32 v[100:101], v[100:101], v[166:167] op_sel_hi:[1,0]
	v_pk_mul_f32 v[92:93], v[92:93], v[164:165] op_sel_hi:[1,0]
	v_pk_mul_f32 v[88:89], v[88:89], v[164:165] op_sel_hi:[1,0]
	v_pk_mul_f32 v[90:91], v[90:91], v[164:165] op_sel_hi:[1,0]
	v_pk_mul_f32 v[84:85], v[84:85], v[164:165] op_sel_hi:[1,0]
	v_pk_mul_f32 v[80:81], v[80:81], v[164:165] op_sel_hi:[1,0]
	v_pk_mul_f32 v[82:83], v[82:83], v[164:165] op_sel_hi:[1,0]
	v_pk_mul_f32 v[76:77], v[76:77], v[158:159] op_sel_hi:[1,0]
	v_pk_mul_f32 v[72:73], v[72:73], v[158:159] op_sel_hi:[1,0]
	v_pk_mul_f32 v[74:75], v[74:75], v[158:159] op_sel_hi:[1,0]
	v_pk_mul_f32 v[68:69], v[68:69], v[158:159] op_sel_hi:[1,0]
	v_pk_mul_f32 v[64:65], v[64:65], v[158:159] op_sel_hi:[1,0]
	v_pk_mul_f32 v[66:67], v[66:67], v[158:159] op_sel_hi:[1,0]
	v_pk_mul_f32 v[60:61], v[60:61], v[154:155] op_sel_hi:[1,0]
	v_pk_mul_f32 v[56:57], v[56:57], v[154:155] op_sel_hi:[1,0]
	v_pk_mul_f32 v[58:59], v[58:59], v[154:155] op_sel_hi:[1,0]
	v_pk_mul_f32 v[52:53], v[52:53], v[154:155] op_sel_hi:[1,0]
	v_pk_mul_f32 v[48:49], v[48:49], v[154:155] op_sel_hi:[1,0]
	v_pk_mul_f32 v[50:51], v[50:51], v[154:155] op_sel_hi:[1,0]
	v_pk_mul_f32 v[44:45], v[44:45], v[150:151] op_sel_hi:[1,0]
	v_pk_mul_f32 v[40:41], v[40:41], v[150:151] op_sel_hi:[1,0]
	v_pk_mul_f32 v[42:43], v[42:43], v[150:151] op_sel_hi:[1,0]
	v_pk_mul_f32 v[36:37], v[36:37], v[150:151] op_sel_hi:[1,0]
	v_pk_mul_f32 v[32:33], v[32:33], v[150:151] op_sel_hi:[1,0]
	v_pk_mul_f32 v[34:35], v[34:35], v[150:151] op_sel_hi:[1,0]
	v_pk_mul_f32 v[28:29], v[28:29], v[146:147] op_sel_hi:[1,0]
	v_pk_mul_f32 v[24:25], v[24:25], v[146:147] op_sel_hi:[1,0]
	v_pk_mul_f32 v[26:27], v[26:27], v[146:147] op_sel_hi:[1,0]
	v_pk_mul_f32 v[20:21], v[20:21], v[146:147] op_sel_hi:[1,0]
	v_pk_mul_f32 v[16:17], v[16:17], v[146:147] op_sel_hi:[1,0]
	v_pk_mul_f32 v[18:19], v[18:19], v[146:147] op_sel_hi:[1,0]
	v_pk_mul_f32 v[12:13], v[12:13], v[96:97] op_sel_hi:[1,0]
	v_pk_mul_f32 v[8:9], v[8:9], v[96:97] op_sel_hi:[1,0]
	v_pk_mul_f32 v[10:11], v[10:11], v[96:97] op_sel_hi:[1,0]
	v_pk_mul_f32 v[4:5], v[4:5], v[96:97] op_sel_hi:[1,0]
	v_pk_mul_f32 v[0:1], v[0:1], v[96:97] op_sel_hi:[1,0]
	v_pk_mul_f32 v[2:3], v[2:3], v[96:97] op_sel_hi:[1,0]
	v_mul_f32_e32 v139, 0xbfb8aa3b, v126
	v_mul_f32_e32 v171, 0xbfb8aa3b, v127
	v_exp_f32_e32 v139, v139
	v_exp_f32_e32 v171, v171
	v_add_f32_e32 v139, 1.0, v139
	v_add_f32_e32 v171, 1.0, v171
	v_rcp_f32_e32 v170, v139
	v_rcp_f32_e32 v171, v171
	s_nop 0
	v_pk_mul_f32 v[126:127], v[126:127], v[170:171]
	s_nop 0
	v_pk_mul_f32 v[122:123], v[122:123], v[126:127]
	v_pk_mul_f32 v[126:127], v[128:129], v[168:169] op_sel_hi:[1,0]
	s_nop 0
	v_mul_f32_e32 v128, 0xbfb8aa3b, v126
	v_mul_f32_e32 v129, 0xbfb8aa3b, v127
	v_exp_f32_e32 v128, v128
	v_exp_f32_e32 v129, v129
	v_add_f32_e32 v128, 1.0, v128
	v_add_f32_e32 v129, 1.0, v129
	v_rcp_f32_e32 v128, v128
	v_rcp_f32_e32 v129, v129
	s_nop 0
	v_pk_mul_f32 v[126:127], v[126:127], v[128:129]
	s_nop 0
	v_pk_mul_f32 v[124:125], v[124:125], v[126:127]
	v_mul_f32_e32 v126, 0xbfb8aa3b, v118
	v_mul_f32_e32 v127, 0xbfb8aa3b, v119
	v_exp_f32_e32 v126, v126
	v_exp_f32_e32 v127, v127
	v_add_f32_e32 v126, 1.0, v126
	v_add_f32_e32 v127, 1.0, v127
	v_rcp_f32_e32 v126, v126
	v_rcp_f32_e32 v127, v127
	s_nop 0
	v_pk_mul_f32 v[118:119], v[118:119], v[126:127]
	s_nop 0
	v_pk_mul_f32 v[114:115], v[114:115], v[118:119]
	v_pk_mul_f32 v[118:119], v[120:121], v[168:169] op_sel_hi:[1,0]
	s_nop 0
	v_mul_f32_e32 v120, 0xbfb8aa3b, v118
	v_mul_f32_e32 v121, 0xbfb8aa3b, v119
	v_exp_f32_e32 v120, v120
	v_exp_f32_e32 v121, v121
	v_add_f32_e32 v120, 1.0, v120
	v_add_f32_e32 v121, 1.0, v121
	v_rcp_f32_e32 v120, v120
	v_rcp_f32_e32 v121, v121
	s_nop 0
	v_pk_mul_f32 v[118:119], v[118:119], v[120:121]
	s_nop 0
	v_pk_mul_f32 v[116:117], v[116:117], v[118:119]
	v_cvt_pk_bf16_f32 v120, v114, v115
	v_mov_b64_e32 v[114:115], s[22:23]
	v_cvt_pk_bf16_f32 v118, v122, v123
	v_cvt_pk_bf16_f32 v121, v116, v117
	v_mad_i64_i32 v[122:123], s[18:19], v160, s15, v[114:115]
	v_lshlrev_b64 v[116:117], 1, v[162:163]
	v_cvt_pk_bf16_f32 v119, v124, v125
	v_lshl_add_u64 v[122:123], v[122:123], 0, v[116:117]
	global_store_dwordx4 v[122:123], v[118:121], off
	s_nop 1
	v_mul_f32_e32 v118, 0xbfb8aa3b, v110
	v_mul_f32_e32 v119, 0xbfb8aa3b, v111
	v_exp_f32_e32 v118, v118
	v_exp_f32_e32 v119, v119
	v_add_f32_e32 v118, 1.0, v118
	v_add_f32_e32 v119, 1.0, v119
	v_rcp_f32_e32 v118, v118
	v_rcp_f32_e32 v119, v119
	s_nop 0
	v_pk_mul_f32 v[110:111], v[110:111], v[118:119]
	s_nop 0
	v_pk_mul_f32 v[106:107], v[106:107], v[110:111]
	v_pk_mul_f32 v[110:111], v[112:113], v[166:167] op_sel_hi:[1,0]
	s_nop 0
	v_mul_f32_e32 v112, 0xbfb8aa3b, v110
	v_mul_f32_e32 v113, 0xbfb8aa3b, v111
	v_exp_f32_e32 v112, v112
	v_exp_f32_e32 v113, v113
	v_add_f32_e32 v112, 1.0, v112
	v_add_f32_e32 v113, 1.0, v113
	v_rcp_f32_e32 v112, v112
	v_rcp_f32_e32 v113, v113
	s_nop 0
	v_pk_mul_f32 v[110:111], v[110:111], v[112:113]
	s_nop 0
	v_pk_mul_f32 v[108:109], v[108:109], v[110:111]
	v_mul_f32_e32 v110, 0xbfb8aa3b, v102
	v_mul_f32_e32 v111, 0xbfb8aa3b, v103
	v_exp_f32_e32 v110, v110
	v_exp_f32_e32 v111, v111
	v_add_f32_e32 v110, 1.0, v110
	v_add_f32_e32 v111, 1.0, v111
	v_rcp_f32_e32 v110, v110
	v_rcp_f32_e32 v111, v111
	s_nop 0
	v_pk_mul_f32 v[102:103], v[102:103], v[110:111]
	s_nop 0
	v_pk_mul_f32 v[102:103], v[98:99], v[102:103]
	v_pk_mul_f32 v[98:99], v[104:105], v[166:167] op_sel_hi:[1,0]
	s_nop 0
	v_mul_f32_e32 v104, 0xbfb8aa3b, v98
	v_mul_f32_e32 v105, 0xbfb8aa3b, v99
	v_exp_f32_e32 v104, v104
	v_exp_f32_e32 v105, v105
	v_add_f32_e32 v104, 1.0, v104
	v_add_f32_e32 v105, 1.0, v105
	v_rcp_f32_e32 v104, v104
	v_rcp_f32_e32 v105, v105
	s_nop 0
	v_pk_mul_f32 v[98:99], v[98:99], v[104:105]
	s_nop 0
	v_pk_mul_f32 v[104:105], v[100:101], v[98:99]
	v_cvt_pk_bf16_f32 v100, v102, v103
	v_mad_i64_i32 v[102:103], s[18:19], v156, s15, v[114:115]
	v_cvt_pk_bf16_f32 v98, v106, v107
	v_cvt_pk_bf16_f32 v99, v108, v109
	v_cvt_pk_bf16_f32 v101, v104, v105
	v_lshl_add_u64 v[102:103], v[102:103], 0, v[116:117]
	global_store_dwordx4 v[102:103], v[98:101], off
	s_nop 1
	v_mul_f32_e32 v98, 0xbfb8aa3b, v92
	v_mul_f32_e32 v99, 0xbfb8aa3b, v93
	v_exp_f32_e32 v98, v98
	v_exp_f32_e32 v99, v99
	v_add_f32_e32 v98, 1.0, v98
	v_add_f32_e32 v99, 1.0, v99
	v_rcp_f32_e32 v98, v98
	v_rcp_f32_e32 v99, v99
	s_nop 0
	v_pk_mul_f32 v[92:93], v[92:93], v[98:99]
	s_nop 0
	v_pk_mul_f32 v[88:89], v[88:89], v[92:93]
	v_pk_mul_f32 v[92:93], v[94:95], v[164:165] op_sel_hi:[1,0]
	s_nop 0
	v_mul_f32_e32 v94, 0xbfb8aa3b, v92
	v_mul_f32_e32 v95, 0xbfb8aa3b, v93
	v_exp_f32_e32 v94, v94
	v_exp_f32_e32 v95, v95
	v_add_f32_e32 v94, 1.0, v94
	v_add_f32_e32 v95, 1.0, v95
	v_rcp_f32_e32 v94, v94
	v_rcp_f32_e32 v95, v95
	s_nop 0
	v_pk_mul_f32 v[92:93], v[92:93], v[94:95]
	s_nop 0
	v_pk_mul_f32 v[90:91], v[90:91], v[92:93]
	v_mul_f32_e32 v92, 0xbfb8aa3b, v84
	v_mul_f32_e32 v93, 0xbfb8aa3b, v85
	v_exp_f32_e32 v92, v92
	v_exp_f32_e32 v93, v93
	v_add_f32_e32 v92, 1.0, v92
	v_add_f32_e32 v93, 1.0, v93
	v_rcp_f32_e32 v92, v92
	v_rcp_f32_e32 v93, v93
	s_nop 0
	v_pk_mul_f32 v[84:85], v[84:85], v[92:93]
	s_nop 0
	v_pk_mul_f32 v[84:85], v[80:81], v[84:85]
	v_pk_mul_f32 v[80:81], v[86:87], v[164:165] op_sel_hi:[1,0]
	s_nop 0
	v_mul_f32_e32 v86, 0xbfb8aa3b, v80
	v_mul_f32_e32 v87, 0xbfb8aa3b, v81
	v_exp_f32_e32 v86, v86
	v_exp_f32_e32 v87, v87
	v_add_f32_e32 v86, 1.0, v86
	v_add_f32_e32 v87, 1.0, v87
	v_rcp_f32_e32 v86, v86
	v_rcp_f32_e32 v87, v87
	s_nop 0
	v_pk_mul_f32 v[80:81], v[80:81], v[86:87]
	s_nop 0
	v_pk_mul_f32 v[86:87], v[82:83], v[80:81]
	v_cvt_pk_bf16_f32 v82, v84, v85
	v_mad_i64_i32 v[84:85], s[18:19], v152, s15, v[114:115]
	v_cvt_pk_bf16_f32 v80, v88, v89
	v_cvt_pk_bf16_f32 v81, v90, v91
	v_cvt_pk_bf16_f32 v83, v86, v87
	v_lshl_add_u64 v[84:85], v[84:85], 0, v[116:117]
	global_store_dwordx4 v[84:85], v[80:83], off
	s_nop 1
	v_mul_f32_e32 v80, 0xbfb8aa3b, v76
	v_mul_f32_e32 v81, 0xbfb8aa3b, v77
	v_exp_f32_e32 v80, v80
	v_exp_f32_e32 v81, v81
	v_add_f32_e32 v80, 1.0, v80
	v_add_f32_e32 v81, 1.0, v81
	v_rcp_f32_e32 v80, v80
	v_rcp_f32_e32 v81, v81
	s_nop 0
	v_pk_mul_f32 v[76:77], v[76:77], v[80:81]
	s_nop 0
	v_pk_mul_f32 v[72:73], v[72:73], v[76:77]
	v_pk_mul_f32 v[76:77], v[78:79], v[158:159] op_sel_hi:[1,0]
	s_nop 0
	v_mul_f32_e32 v78, 0xbfb8aa3b, v76
	v_mul_f32_e32 v79, 0xbfb8aa3b, v77
	v_exp_f32_e32 v78, v78
	v_exp_f32_e32 v79, v79
	v_add_f32_e32 v78, 1.0, v78
	v_add_f32_e32 v79, 1.0, v79
	v_rcp_f32_e32 v78, v78
	v_rcp_f32_e32 v79, v79
	s_nop 0
	v_pk_mul_f32 v[76:77], v[76:77], v[78:79]
	s_nop 0
	v_pk_mul_f32 v[74:75], v[74:75], v[76:77]
	v_mul_f32_e32 v76, 0xbfb8aa3b, v68
	v_mul_f32_e32 v77, 0xbfb8aa3b, v69
	v_exp_f32_e32 v76, v76
	v_exp_f32_e32 v77, v77
	v_add_f32_e32 v76, 1.0, v76
	v_add_f32_e32 v77, 1.0, v77
	v_rcp_f32_e32 v76, v76
	v_rcp_f32_e32 v77, v77
	s_nop 0
	v_pk_mul_f32 v[68:69], v[68:69], v[76:77]
	s_nop 0
	v_pk_mul_f32 v[68:69], v[64:65], v[68:69]
	v_pk_mul_f32 v[64:65], v[70:71], v[158:159] op_sel_hi:[1,0]
	s_nop 0
	v_mul_f32_e32 v70, 0xbfb8aa3b, v64
	v_mul_f32_e32 v71, 0xbfb8aa3b, v65
	v_exp_f32_e32 v70, v70
	v_exp_f32_e32 v71, v71
	v_add_f32_e32 v70, 1.0, v70
	v_add_f32_e32 v71, 1.0, v71
	v_rcp_f32_e32 v70, v70
	v_rcp_f32_e32 v71, v71
	s_nop 0
	v_pk_mul_f32 v[64:65], v[64:65], v[70:71]
	s_nop 0
	v_pk_mul_f32 v[70:71], v[66:67], v[64:65]
	v_cvt_pk_bf16_f32 v66, v68, v69
	v_mad_i64_i32 v[68:69], s[18:19], v148, s15, v[114:115]
	v_cvt_pk_bf16_f32 v64, v72, v73
	v_cvt_pk_bf16_f32 v65, v74, v75
	v_cvt_pk_bf16_f32 v67, v70, v71
	v_lshl_add_u64 v[68:69], v[68:69], 0, v[116:117]
	global_store_dwordx4 v[68:69], v[64:67], off
	s_nop 1
	v_mul_f32_e32 v64, 0xbfb8aa3b, v60
	v_mul_f32_e32 v65, 0xbfb8aa3b, v61
	v_exp_f32_e32 v64, v64
	v_exp_f32_e32 v65, v65
	v_add_f32_e32 v64, 1.0, v64
	v_add_f32_e32 v65, 1.0, v65
	v_rcp_f32_e32 v64, v64
	v_rcp_f32_e32 v65, v65
	s_nop 0
	v_pk_mul_f32 v[60:61], v[60:61], v[64:65]
	s_nop 0
	v_pk_mul_f32 v[56:57], v[56:57], v[60:61]
	v_pk_mul_f32 v[60:61], v[62:63], v[154:155] op_sel_hi:[1,0]
	s_nop 0
	v_mul_f32_e32 v62, 0xbfb8aa3b, v60
	v_mul_f32_e32 v63, 0xbfb8aa3b, v61
	v_exp_f32_e32 v62, v62
	v_exp_f32_e32 v63, v63
	v_add_f32_e32 v62, 1.0, v62
	v_add_f32_e32 v63, 1.0, v63
	v_rcp_f32_e32 v62, v62
	v_rcp_f32_e32 v63, v63
	s_nop 0
	v_pk_mul_f32 v[60:61], v[60:61], v[62:63]
	s_nop 0
	v_pk_mul_f32 v[58:59], v[58:59], v[60:61]
	v_mul_f32_e32 v60, 0xbfb8aa3b, v52
	v_mul_f32_e32 v61, 0xbfb8aa3b, v53
	v_exp_f32_e32 v60, v60
	v_exp_f32_e32 v61, v61
	v_add_f32_e32 v60, 1.0, v60
	v_add_f32_e32 v61, 1.0, v61
	v_rcp_f32_e32 v60, v60
	v_rcp_f32_e32 v61, v61
	s_nop 0
	v_pk_mul_f32 v[52:53], v[52:53], v[60:61]
	s_nop 0
	v_pk_mul_f32 v[52:53], v[48:49], v[52:53]
	v_pk_mul_f32 v[48:49], v[54:55], v[154:155] op_sel_hi:[1,0]
	s_nop 0
	v_mul_f32_e32 v54, 0xbfb8aa3b, v48
	v_mul_f32_e32 v55, 0xbfb8aa3b, v49
	v_exp_f32_e32 v54, v54
	v_exp_f32_e32 v55, v55
	v_add_f32_e32 v54, 1.0, v54
	v_add_f32_e32 v55, 1.0, v55
	v_rcp_f32_e32 v54, v54
	v_rcp_f32_e32 v55, v55
	s_nop 0
	v_pk_mul_f32 v[48:49], v[48:49], v[54:55]
	s_nop 0
	v_pk_mul_f32 v[54:55], v[50:51], v[48:49]
	v_cvt_pk_bf16_f32 v50, v52, v53
	v_mad_i64_i32 v[52:53], s[18:19], v144, s15, v[114:115]
	v_cvt_pk_bf16_f32 v48, v56, v57
	v_cvt_pk_bf16_f32 v49, v58, v59
	v_cvt_pk_bf16_f32 v51, v54, v55
	v_lshl_add_u64 v[52:53], v[52:53], 0, v[116:117]
	global_store_dwordx4 v[52:53], v[48:51], off
	s_nop 1
	v_mul_f32_e32 v48, 0xbfb8aa3b, v44
	v_mul_f32_e32 v49, 0xbfb8aa3b, v45
	v_exp_f32_e32 v48, v48
	v_exp_f32_e32 v49, v49
	v_add_f32_e32 v48, 1.0, v48
	v_add_f32_e32 v49, 1.0, v49
	v_rcp_f32_e32 v48, v48
	v_rcp_f32_e32 v49, v49
	s_nop 0
	v_pk_mul_f32 v[44:45], v[44:45], v[48:49]
	s_nop 0
	v_pk_mul_f32 v[40:41], v[40:41], v[44:45]
	v_pk_mul_f32 v[44:45], v[46:47], v[150:151] op_sel_hi:[1,0]
	s_nop 0
	v_mul_f32_e32 v46, 0xbfb8aa3b, v44
	v_mul_f32_e32 v47, 0xbfb8aa3b, v45
	v_exp_f32_e32 v46, v46
	v_exp_f32_e32 v47, v47
	v_add_f32_e32 v46, 1.0, v46
	v_add_f32_e32 v47, 1.0, v47
	v_rcp_f32_e32 v46, v46
	v_rcp_f32_e32 v47, v47
	s_nop 0
	v_pk_mul_f32 v[44:45], v[44:45], v[46:47]
	s_nop 0
	v_pk_mul_f32 v[42:43], v[42:43], v[44:45]
	v_mul_f32_e32 v44, 0xbfb8aa3b, v36
	v_mul_f32_e32 v45, 0xbfb8aa3b, v37
	v_exp_f32_e32 v44, v44
	v_exp_f32_e32 v45, v45
	v_add_f32_e32 v44, 1.0, v44
	v_add_f32_e32 v45, 1.0, v45
	v_rcp_f32_e32 v44, v44
	v_rcp_f32_e32 v45, v45
	s_nop 0
	v_pk_mul_f32 v[36:37], v[36:37], v[44:45]
	s_nop 0
	v_pk_mul_f32 v[36:37], v[32:33], v[36:37]
	v_pk_mul_f32 v[32:33], v[38:39], v[150:151] op_sel_hi:[1,0]
	s_nop 0
	v_mul_f32_e32 v38, 0xbfb8aa3b, v32
	v_mul_f32_e32 v39, 0xbfb8aa3b, v33
	v_exp_f32_e32 v38, v38
	v_exp_f32_e32 v39, v39
	v_add_f32_e32 v38, 1.0, v38
	v_add_f32_e32 v39, 1.0, v39
	v_rcp_f32_e32 v38, v38
	v_rcp_f32_e32 v39, v39
	s_nop 0
	v_pk_mul_f32 v[32:33], v[32:33], v[38:39]
	s_nop 0
	v_pk_mul_f32 v[38:39], v[34:35], v[32:33]
	v_cvt_pk_bf16_f32 v34, v36, v37
	v_mad_i64_i32 v[36:37], s[18:19], v142, s15, v[114:115]
	v_cvt_pk_bf16_f32 v32, v40, v41
	v_cvt_pk_bf16_f32 v33, v42, v43
	v_cvt_pk_bf16_f32 v35, v38, v39
	v_lshl_add_u64 v[36:37], v[36:37], 0, v[116:117]
	global_store_dwordx4 v[36:37], v[32:35], off
	s_nop 1
	v_mul_f32_e32 v32, 0xbfb8aa3b, v28
	v_mul_f32_e32 v33, 0xbfb8aa3b, v29
	v_exp_f32_e32 v32, v32
	v_exp_f32_e32 v33, v33
	v_add_f32_e32 v32, 1.0, v32
	v_add_f32_e32 v33, 1.0, v33
	v_rcp_f32_e32 v32, v32
	v_rcp_f32_e32 v33, v33
	s_nop 0
	v_pk_mul_f32 v[28:29], v[28:29], v[32:33]
	s_nop 0
	v_pk_mul_f32 v[24:25], v[24:25], v[28:29]
	v_pk_mul_f32 v[28:29], v[30:31], v[146:147] op_sel_hi:[1,0]
	s_nop 0
	v_mul_f32_e32 v30, 0xbfb8aa3b, v28
	v_mul_f32_e32 v31, 0xbfb8aa3b, v29
	v_exp_f32_e32 v30, v30
	v_exp_f32_e32 v31, v31
	v_add_f32_e32 v30, 1.0, v30
	v_add_f32_e32 v31, 1.0, v31
	v_rcp_f32_e32 v30, v30
	v_rcp_f32_e32 v31, v31
	s_nop 0
	v_pk_mul_f32 v[28:29], v[28:29], v[30:31]
	s_nop 0
	v_pk_mul_f32 v[26:27], v[26:27], v[28:29]
	v_mul_f32_e32 v28, 0xbfb8aa3b, v20
	v_mul_f32_e32 v29, 0xbfb8aa3b, v21
	v_exp_f32_e32 v28, v28
	v_exp_f32_e32 v29, v29
	v_add_f32_e32 v28, 1.0, v28
	v_add_f32_e32 v29, 1.0, v29
	v_rcp_f32_e32 v28, v28
	v_rcp_f32_e32 v29, v29
	s_nop 0
	v_pk_mul_f32 v[20:21], v[20:21], v[28:29]
	s_nop 0
	v_pk_mul_f32 v[20:21], v[16:17], v[20:21]
	v_pk_mul_f32 v[16:17], v[22:23], v[146:147] op_sel_hi:[1,0]
	s_nop 0
	v_mul_f32_e32 v22, 0xbfb8aa3b, v16
	v_mul_f32_e32 v23, 0xbfb8aa3b, v17
	v_exp_f32_e32 v22, v22
	v_exp_f32_e32 v23, v23
	v_add_f32_e32 v22, 1.0, v22
	v_add_f32_e32 v23, 1.0, v23
	v_rcp_f32_e32 v22, v22
	v_rcp_f32_e32 v23, v23
	s_nop 0
	v_pk_mul_f32 v[16:17], v[16:17], v[22:23]
	s_nop 0
	v_pk_mul_f32 v[22:23], v[18:19], v[16:17]
	v_cvt_pk_bf16_f32 v18, v20, v21
	v_mad_i64_i32 v[20:21], s[18:19], v140, s15, v[114:115]
	v_cvt_pk_bf16_f32 v16, v24, v25
	v_cvt_pk_bf16_f32 v17, v26, v27
	v_cvt_pk_bf16_f32 v19, v22, v23
	v_lshl_add_u64 v[20:21], v[20:21], 0, v[116:117]
	global_store_dwordx4 v[20:21], v[16:19], off
	s_nop 1
	v_mul_f32_e32 v16, 0xbfb8aa3b, v12
	v_mul_f32_e32 v17, 0xbfb8aa3b, v13
	v_exp_f32_e32 v16, v16
	v_exp_f32_e32 v17, v17
	v_add_f32_e32 v16, 1.0, v16
	v_add_f32_e32 v17, 1.0, v17
	v_rcp_f32_e32 v16, v16
	v_rcp_f32_e32 v17, v17
	s_nop 0
	v_pk_mul_f32 v[12:13], v[12:13], v[16:17]
	s_nop 0
	v_pk_mul_f32 v[8:9], v[8:9], v[12:13]
	v_pk_mul_f32 v[12:13], v[14:15], v[96:97] op_sel_hi:[1,0]
	s_nop 0
	v_mul_f32_e32 v14, 0xbfb8aa3b, v12
	v_mul_f32_e32 v15, 0xbfb8aa3b, v13
	v_exp_f32_e32 v14, v14
	v_exp_f32_e32 v15, v15
	v_add_f32_e32 v14, 1.0, v14
	v_add_f32_e32 v15, 1.0, v15
	v_rcp_f32_e32 v14, v14
	v_rcp_f32_e32 v15, v15
	s_nop 0
	v_pk_mul_f32 v[12:13], v[12:13], v[14:15]
	s_nop 0
	v_pk_mul_f32 v[10:11], v[10:11], v[12:13]
	v_mul_f32_e32 v12, 0xbfb8aa3b, v4
	v_mul_f32_e32 v13, 0xbfb8aa3b, v5
	v_exp_f32_e32 v12, v12
	v_exp_f32_e32 v13, v13
	v_add_f32_e32 v12, 1.0, v12
	v_add_f32_e32 v13, 1.0, v13
	v_rcp_f32_e32 v12, v12
	v_rcp_f32_e32 v13, v13
	s_nop 0
	v_pk_mul_f32 v[4:5], v[4:5], v[12:13]
	s_nop 0
	v_pk_mul_f32 v[4:5], v[0:1], v[4:5]
	v_pk_mul_f32 v[0:1], v[6:7], v[96:97] op_sel_hi:[1,0]
	s_nop 0
	v_mul_f32_e32 v6, 0xbfb8aa3b, v0
	v_mul_f32_e32 v7, 0xbfb8aa3b, v1
	v_exp_f32_e32 v6, v6
	v_exp_f32_e32 v7, v7
	v_add_f32_e32 v6, 1.0, v6
	v_add_f32_e32 v7, 1.0, v7
	v_rcp_f32_e32 v6, v6
	v_rcp_f32_e32 v7, v7
	s_nop 0
	v_pk_mul_f32 v[0:1], v[0:1], v[6:7]
	s_nop 0
	v_pk_mul_f32 v[6:7], v[2:3], v[0:1]
	v_cvt_pk_bf16_f32 v2, v4, v5
	v_mad_i64_i32 v[4:5], s[18:19], v138, s15, v[114:115]
	v_cvt_pk_bf16_f32 v0, v8, v9
	v_cvt_pk_bf16_f32 v1, v10, v11
	v_cvt_pk_bf16_f32 v3, v6, v7
	v_lshl_add_u64 v[4:5], v[4:5], 0, v[116:117]
	global_store_dwordx4 v[4:5], v[0:3], off
	s_cbranch_vccnz .LBB0_736
	s_andn2_b64 vcc, exec, s[8:9]
	s_cbranch_vccnz .LBB0_735
	s_barrier
	s_branch .LBB0_735
